# m3 + FFN-down LN normalise: (1+scale) and shift vectors of a block loaded together under one wait (was load, full wait, load)
# baseline (speedup 1.0000x reference)
.LBB0_576:
	s_or_b64 exec, exec, s[8:9]
	s_lshl_b32 s8, s17, 12
	s_add_u32 s0, s48, s8
	s_addc_u32 s1, s49, 0
	s_add_u32 s8, s50, s8
	s_addc_u32 s9, s51, 0
	s_waitcnt lgkmcnt(0)
	s_barrier
	v_lshl_add_u64 v[178:179], s[0:1], 0, v[142:143]
	v_lshl_add_u64 v[180:181], s[8:9], 0, v[142:143]
	global_load_dwordx4 v[130:133], v[178:179], off
	global_load_dwordx4 v[134:137], v[180:181], off
	s_add_u32 s8, s56, 0x104000
	s_addc_u32 s9, s57, 0
	s_add_u32 s10, s56, 0x103000
	s_addc_u32 s11, s57, 0
	v_mov_b32_e32 v170, 0
	s_and_b64 vcc, s[46:47], exec
	v_mov_b32_e32 v171, 0
	v_mov_b32_e32 v172, 0
	v_mov_b32_e32 v173, 0
	v_mov_b32_e32 v138, 0
	v_mov_b32_e32 v139, 0
	v_mov_b32_e32 v140, 0
	v_mov_b32_e32 v141, 0
	s_cbranch_vccz .LBB0_578
	s_add_u32 s0, s10, s62
	s_addc_u32 s1, s11, s63
	v_lshl_add_u64 v[164:165], s[0:1], 0, v[142:143]
	s_add_u32 s0, s8, s62
	s_addc_u32 s1, s9, s63
	v_lshl_add_u64 v[138:139], s[0:1], 0, v[142:143]
	global_load_dwordx4 v[226:229], v[138:139], off
	global_load_dwordx4 v[138:141], v[164:165], off
	s_waitcnt vmcnt(0)
	v_pk_add_f32 v[172:173], v[228:229], 1.0 op_sel_hi:[1,0]
	v_pk_add_f32 v[170:171], v[226:227], 1.0 op_sel_hi:[1,0]

.LBB0_594:
	global_load_dwordx4 v[66:69], v[178:179], off offset:64
	s_nop 0
	global_load_dwordx4 v[78:81], v[180:181], off offset:64
	v_mov_b32_e32 v210, 0
	s_and_b64 vcc, exec, s[38:39]
	v_mov_b32_e32 v211, 0
	v_mov_b32_e32 v212, 0
	v_mov_b32_e32 v213, 0
	v_mov_b32_e32 v94, 0
	v_mov_b32_e32 v95, 0
	v_mov_b32_e32 v96, 0
	v_mov_b32_e32 v97, 0
	s_cbranch_vccnz .LBB0_596
	s_add_u32 s0, s10, s62
	s_addc_u32 s1, s11, s63
	v_lshl_add_u64 v[134:135], s[0:1], 0, v[142:143]
	s_add_u32 s0, s8, s62
	s_addc_u32 s1, s9, s63
	v_lshl_add_u64 v[94:95], s[0:1], 0, v[142:143]
	global_load_dwordx4 v[226:229], v[94:95], off offset:64
	global_load_dwordx4 v[94:97], v[134:135], off offset:64
	s_waitcnt vmcnt(0)
	v_pk_add_f32 v[212:213], v[228:229], 1.0 op_sel_hi:[1,0]
	v_pk_add_f32 v[210:211], v[226:227], 1.0 op_sel_hi:[1,0]

.LBB0_612:
	global_load_dwordx4 v[34:37], v[178:179], off offset:512
	s_nop 0
	global_load_dwordx4 v[46:49], v[180:181], off offset:512
	v_mov_b32_e32 v210, 0
	s_and_b64 vcc, exec, s[38:39]
	v_mov_b32_e32 v211, 0
	v_mov_b32_e32 v212, 0
	v_mov_b32_e32 v213, 0
	v_mov_b32_e32 v62, 0
	v_mov_b32_e32 v63, 0
	v_mov_b32_e32 v64, 0
	v_mov_b32_e32 v65, 0
	s_cbranch_vccnz .LBB0_614
	s_add_u32 s0, s10, s62
	s_addc_u32 s1, s11, s63
	v_lshl_add_u64 v[78:79], s[0:1], 0, v[142:143]
	s_add_u32 s0, s8, s62
	s_addc_u32 s1, s9, s63
	v_lshl_add_u64 v[62:63], s[0:1], 0, v[142:143]
	global_load_dwordx4 v[226:229], v[62:63], off offset:512
	global_load_dwordx4 v[62:65], v[78:79], off offset:512
	s_waitcnt vmcnt(0)
	v_pk_add_f32 v[212:213], v[228:229], 1.0 op_sel_hi:[1,0]
	v_pk_add_f32 v[210:211], v[226:227], 1.0 op_sel_hi:[1,0]

.LBB0_630:
	global_load_dwordx4 v[14:17], v[178:179], off offset:576
	s_nop 0
	global_load_dwordx4 v[22:25], v[180:181], off offset:576
	v_mov_b32_e32 v62, 0
	s_and_b64 vcc, exec, s[38:39]
	v_mov_b32_e32 v63, 0
	v_mov_b32_e32 v64, 0
	v_mov_b32_e32 v65, 0
	v_mov_b32_e32 v30, 0
	v_mov_b32_e32 v31, 0
	v_mov_b32_e32 v32, 0
	v_mov_b32_e32 v33, 0
	s_cbranch_vccnz .LBB0_632
	s_add_u32 s0, s10, s62
	s_addc_u32 s1, s11, s63
	v_lshl_add_u64 v[46:47], s[0:1], 0, v[142:143]
	s_add_u32 s0, s8, s62
	s_addc_u32 s1, s9, s63
	v_lshl_add_u64 v[30:31], s[0:1], 0, v[142:143]
	global_load_dwordx4 v[226:229], v[30:31], off offset:576
	global_load_dwordx4 v[30:33], v[46:47], off offset:576
	s_waitcnt vmcnt(0)
	v_pk_add_f32 v[64:65], v[228:229], 1.0 op_sel_hi:[1,0]
	v_pk_add_f32 v[62:63], v[226:227], 1.0 op_sel_hi:[1,0]
